# v16 + nt on x row loads (init), H row loads (final), S5 matrix stores (prologue)
# speedup vs baseline: 1.0021x; 1.0020x over previous
.LBB0_48:
	s_or_b64 exec, exec, s[18:19]
	s_waitcnt lgkmcnt(1)
	v_bfe_u32 v23, v2, 16, 1
	v_add3_u32 v2, v2, v23, s22
	v_bfe_u32 v23, v3, 16, 1
	v_lshrrev_b32_e32 v2, 16, v2
	v_add3_u32 v3, v3, v23, s22
	v_and_or_b32 v2, v3, s23, v2
	v_bfe_u32 v3, v4, 16, 1
	v_add3_u32 v3, v4, v3, s22
	v_bfe_u32 v4, v5, 16, 1
	v_lshrrev_b32_e32 v3, 16, v3
	v_add3_u32 v4, v5, v4, s22
	v_and_or_b32 v3, v4, s23, v3
	s_waitcnt lgkmcnt(0)
	v_bfe_u32 v4, v6, 16, 1
	v_add3_u32 v4, v6, v4, s22
	v_bfe_u32 v5, v7, 16, 1
	v_lshrrev_b32_e32 v4, 16, v4
	v_add3_u32 v5, v7, v5, s22
	v_and_or_b32 v4, v5, s23, v4
	v_bfe_u32 v5, v8, 16, 1
	v_add3_u32 v5, v8, v5, s22
	v_bfe_u32 v6, v9, 16, 1
	v_lshrrev_b32_e32 v5, 16, v5
	v_add3_u32 v6, v9, v6, s22
	v_ashrrev_i32_e32 v23, 31, v22
	v_and_or_b32 v5, v6, s23, v5
	v_lshlrev_b64 v[6:7], 10, v[22:23]
	v_lshl_add_u64 v[6:7], v[20:21], 0, v[6:7]
	global_store_dwordx4 v[6:7], v[2:5], off nt
	v_cmp_lt_i32_e32 vcc, s33, v31
	v_add_u32_e32 v30, 0x1000, v30
	v_add_u32_e32 v2, 0x200, v31
	s_or_b64 s[14:15], vcc, s[14:15]
	v_mov_b32_e32 v31, v2
	s_andn2_b64 exec, exec, s[14:15]
	s_cbranch_execz .LBB0_51

.LBB0_52:
	v_ashrrev_i32_e32 v4, 5, v3
	v_and_b32_e32 v6, 16, v3
	v_ashrrev_i32_e32 v5, 9, v3
	v_lshlrev_b32_e32 v7, 3, v2
	v_and_or_b32 v6, v4, 15, v6
	v_add_u32_e32 v8, 0x200, v3
	v_add_u32_e32 v9, 1, v5
	v_sub_u32_e32 v22, 16, v5
	v_and_b32_e32 v7, 0x1e0, v7
	v_ashrrev_i32_e32 v5, 31, v4
	v_mul_u32_u24_e32 v6, 0x208, v6
	v_cmp_lt_i32_e32 vcc, s33, v3
	v_mov_b32_e32 v3, v8
	v_cndmask_b32_e64 v8, v22, v9, s[10:11]
	v_lshlrev_b64 v[4:5], 10, v[4:5]
	v_add3_u32 v6, 0, v6, v7
	v_add_lshl_u32 v22, v8, v24, 9
	v_lshl_add_u64 v[8:9], v[20:21], 0, v[4:5]
	v_add_u32_e32 v4, 0x8400, v6
	v_add3_u32 v22, 0, v22, v7
	v_add_u32_e32 v23, 0x8410, v6
	ds_read2_b64 v[4:7], v4 offset1:1
	ds_read_b128 v[30:33], v22
	ds_read_b128 v[34:37], v22 offset:16
	ds_read2_b64 v[38:41], v23 offset1:1
	v_add_u32_e32 v2, 0x800, v2
	s_waitcnt lgkmcnt(3)
	v_mov_b32_e32 v23, v6
	s_waitcnt lgkmcnt(2)
	v_mov_b32_e32 v42, v30
	v_mov_b32_e32 v43, v32
	v_mov_b32_e32 v6, v5
	v_mov_b32_e32 v32, v31
	s_waitcnt lgkmcnt(0)
	v_mov_b32_e32 v5, v40
	v_mov_b32_e32 v30, v34
	v_mov_b32_e32 v31, v36
	v_mov_b32_e32 v40, v39
	v_mov_b32_e32 v36, v35
	v_mov_b32_e32 v22, v4
	v_mov_b32_e32 v4, v38
	v_pk_mul_f32 v[34:35], v[6:7], v[32:33]
	v_pk_mul_f32 v[6:7], v[6:7], v[42:43]
	v_pk_mul_f32 v[38:39], v[40:41], v[36:37]
	v_pk_mul_f32 v[40:41], v[40:41], v[30:31]
	v_pk_fma_f32 v[34:35], v[22:23], v[42:43], v[34:35] neg_lo:[0,0,1] neg_hi:[0,0,1]
	v_pk_fma_f32 v[6:7], v[22:23], v[32:33], v[6:7]
	v_pk_fma_f32 v[22:23], v[4:5], v[30:31], v[38:39] neg_lo:[0,0,1] neg_hi:[0,0,1]
	v_pk_fma_f32 v[4:5], v[4:5], v[36:37], v[40:41]
	v_pk_add_f32 v[6:7], v[6:7], 0 neg_lo:[1,1] neg_hi:[1,1]
	v_pk_add_f32 v[4:5], v[4:5], 0 neg_lo:[1,1] neg_hi:[1,1]
	v_bfe_u32 v30, v34, 16, 1
	v_bfe_u32 v31, v35, 16, 1
	v_bfe_u32 v32, v22, 16, 1
	v_bfe_u32 v33, v23, 16, 1
	v_bfe_u32 v36, v5, 16, 1
	v_bfe_u32 v37, v4, 16, 1
	v_bfe_u32 v38, v7, 16, 1
	v_bfe_u32 v39, v6, 16, 1
	v_add3_u32 v23, v23, v33, s22
	v_add3_u32 v22, v22, v32, s22
	v_add3_u32 v31, v35, v31, s22
	v_add3_u32 v30, v34, v30, s22
	v_add3_u32 v32, v6, v39, s22
	v_add3_u32 v33, v7, v38, s22
	v_add3_u32 v4, v4, v37, s22
	v_add3_u32 v5, v5, v36, s22
	v_lshrrev_b32_e32 v30, 16, v30
	v_lshrrev_b32_e32 v31, 16, v31
	v_lshrrev_b32_e32 v6, 16, v22
	v_lshrrev_b32_e32 v7, 16, v23
	s_or_b64 s[14:15], vcc, s[14:15]
	v_and_or_b32 v7, v5, s23, v7
	v_and_or_b32 v6, v4, s23, v6
	v_and_or_b32 v5, v33, s23, v31
	v_and_or_b32 v4, v32, s23, v30
	global_store_dwordx4 v[8:9], v[4:7], off offset:512 nt
	s_andn2_b64 exec, exec, s[14:15]
	s_cbranch_execnz .LBB0_52
	s_or_b64 exec, exec, s[14:15]
	s_lshl_b64 s[0:1], s[46:47], 17
	v_lshl_add_u64 v[2:3], v[16:17], 0, s[0:1]
	s_mov_b64 s[18:19], 0
	v_mov_b32_e32 v4, v27
	v_mov_b32_e32 v5, v1
.LBB0_54:
	v_ashrrev_i32_e32 v6, 5, v5
	v_ashrrev_i32_e32 v7, 12, v5
	v_cmp_gt_u32_e32 vcc, s29, v5
	v_and_b32_e32 v8, 8, v4
	v_and_b32_e32 v9, 32, v5
	v_add_u32_e32 v20, 0x200, v5
	v_cndmask_b32_e32 v21, v15, v25, vcc
	v_bfe_u32 v22, v6, 1, 6
	v_mul_i32_i24_e32 v23, 17, v7
	v_cmp_lt_i32_e64 s[14:15], s33, v5
	v_lshl_add_u32 v30, v7, 13, 0
	v_lshlrev_b32_e32 v8, 3, v8
	v_ashrrev_i32_e32 v7, 31, v6
	v_mov_b32_e32 v5, v20
	v_cmp_eq_u32_e32 vcc, 0, v9
	v_add_lshl_u32 v9, v21, v23, 9
	v_lshlrev_b32_e32 v20, 3, v22
	v_lshlrev_b32_e32 v21, 7, v22
	v_lshlrev_b64 v[6:7], 9, v[6:7]
	v_add3_u32 v31, 0, v9, v20
	v_add3_u32 v34, v30, v21, v8
	v_lshl_add_u64 v[38:39], v[2:3], 0, v[6:7]
	ds_read_b128 v[6:9], v34 offset:17408
	ds_read_b128 v[20:23], v34 offset:17424
	ds_read_b64 v[40:41], v31
	ds_read_b128 v[30:33], v34 offset:17440
	ds_read_b128 v[34:37], v34 offset:17456
	s_waitcnt lgkmcnt(4)
	v_mov_b32_e32 v42, v6
	s_waitcnt lgkmcnt(3)
	v_mov_b32_e32 v43, v20
	v_mov_b32_e32 v44, v7
	v_mov_b32_e32 v45, v21
	v_mov_b32_e32 v50, v6
	v_mov_b32_e32 v51, v21
	v_pk_mov_b32 v[6:7], v[6:7], v[20:21] op_sel:[1,0]
	v_mov_b32_e32 v20, v8
	v_mov_b32_e32 v21, v22
	v_mov_b32_e32 v54, v9
	v_mov_b32_e32 v55, v23
	v_mov_b32_e32 v56, v8
	v_pk_mov_b32 v[8:9], v[8:9], v[22:23] op_sel:[1,0]
	s_waitcnt lgkmcnt(1)
	v_mov_b32_e32 v22, v30
	v_mov_b32_e32 v58, v31
	s_waitcnt lgkmcnt(0)
	v_mov_b32_e32 v59, v35
	v_mov_b32_e32 v66, v30
	v_pk_mov_b32 v[30:31], v[30:31], v[34:35] op_sel:[1,0]
	v_mov_b32_e32 v57, v23
	v_mov_b32_e32 v23, v34
	v_mov_b32_e32 v67, v35
	v_mov_b32_e32 v34, v32
	v_mov_b32_e32 v35, v36
	v_mov_b32_e32 v68, v33
	v_mov_b32_e32 v69, v37
	v_mov_b32_e32 v70, v32
	v_mov_b32_e32 v71, v37
	v_pk_mov_b32 v[32:33], v[32:33], v[36:37] op_sel:[1,0]
	v_pk_mul_f32 v[36:37], v[40:41], v[44:45] op_sel:[1,0]
	v_pk_mul_f32 v[6:7], v[40:41], v[6:7]
	v_pk_mul_f32 v[44:45], v[40:41], v[54:55] op_sel:[1,0]
	v_pk_mul_f32 v[8:9], v[40:41], v[8:9]
	v_pk_mul_f32 v[54:55], v[40:41], v[58:59] op_sel:[1,0]
	v_pk_mul_f32 v[30:31], v[40:41], v[30:31]
	v_pk_mul_f32 v[58:59], v[40:41], v[68:69] op_sel:[1,0]
	v_pk_mul_f32 v[32:33], v[40:41], v[32:33]
	v_pk_fma_f32 v[36:37], v[40:41], v[42:43], v[36:37] op_sel_hi:[0,1,1] neg_lo:[0,0,1] neg_hi:[0,0,1]
	v_pk_fma_f32 v[6:7], v[40:41], v[50:51], v[6:7] op_sel:[1,0,0] op_sel_hi:[0,1,1]
	v_pk_fma_f32 v[20:21], v[40:41], v[20:21], v[44:45] op_sel_hi:[0,1,1] neg_lo:[0,0,1] neg_hi:[0,0,1]
	v_pk_fma_f32 v[8:9], v[40:41], v[56:57], v[8:9] op_sel:[1,0,0] op_sel_hi:[0,1,1]
	v_pk_fma_f32 v[22:23], v[40:41], v[22:23], v[54:55] op_sel_hi:[0,1,1] neg_lo:[0,0,1] neg_hi:[0,0,1]
	v_pk_fma_f32 v[30:31], v[40:41], v[66:67], v[30:31] op_sel:[1,0,0] op_sel_hi:[0,1,1]
	v_pk_fma_f32 v[34:35], v[40:41], v[34:35], v[58:59] op_sel_hi:[0,1,1] neg_lo:[0,0,1] neg_hi:[0,0,1]
	v_pk_fma_f32 v[32:33], v[40:41], v[70:71], v[32:33] op_sel:[1,0,0] op_sel_hi:[0,1,1]
	v_cndmask_b32_e32 v7, v7, v37, vcc
	v_cndmask_b32_e32 v6, v6, v36, vcc
	v_cndmask_b32_e32 v8, v8, v20, vcc
	v_cndmask_b32_e32 v9, v9, v21, vcc
	v_cndmask_b32_e32 v20, v31, v23, vcc
	v_cndmask_b32_e32 v21, v30, v22, vcc
	v_cndmask_b32_e32 v22, v32, v34, vcc
	v_cndmask_b32_e32 v23, v33, v35, vcc
	v_bfe_u32 v34, v6, 16, 1
	v_bfe_u32 v35, v7, 16, 1
	v_bfe_u32 v36, v21, 16, 1
	v_bfe_u32 v37, v20, 16, 1
	v_bfe_u32 v30, v23, 16, 1
	v_bfe_u32 v31, v22, 16, 1
	v_bfe_u32 v32, v9, 16, 1
	v_bfe_u32 v33, v8, 16, 1
	v_add3_u32 v20, v20, v37, s22
	v_add3_u32 v21, v21, v36, s22
	v_add3_u32 v7, v7, v35, s22
	v_add3_u32 v6, v6, v34, s22
	v_add3_u32 v33, v8, v33, s22
	v_add3_u32 v32, v9, v32, s22
	v_add3_u32 v8, v22, v31, s22
	v_add3_u32 v9, v23, v30, s22
	v_lshrrev_b32_e32 v6, 16, v6
	v_lshrrev_b32_e32 v7, 16, v7
	v_lshrrev_b32_e32 v21, 16, v21
	v_lshrrev_b32_e32 v20, 16, v20
	v_add_u32_e32 v4, 0x1000, v4
	s_or_b64 s[18:19], s[14:15], s[18:19]
	v_and_or_b32 v9, v9, s23, v20
	v_and_or_b32 v8, v8, s23, v21
	v_and_or_b32 v7, v32, s23, v7
	v_and_or_b32 v6, v33, s23, v6
	global_store_dwordx4 v[38:39], v[6:9], off nt
	s_andn2_b64 exec, exec, s[18:19]
	s_cbranch_execnz .LBB0_54
	s_branch .LBB0_19

.LBB0_1791:
	s_or_b64 exec, exec, s[36:37]
	v_readlane_b32 s0, v255, 6
	v_readlane_b32 s1, v255, 7
	s_mov_b64 s[2:3], -1
	s_and_b64 vcc, exec, s[0:1]
	s_waitcnt lgkmcnt(0)
	s_barrier
	s_cbranch_vccz .LBB0_1798
	v_mov_b32_e32 v2, v56
	v_readlane_b32 s1, v254, 50
	v_readfirstlane_b32 s0, v2
	s_ashr_i32 s0, s0, 6
	s_add_i32 s4, s0, s1
	s_cmpk_gt_i32 s4, 0x3fff
	s_cbranch_scc1 .LBB0_1797
	v_readlane_b32 s16, v251, 6
	v_readlane_b32 s20, v251, 10
	v_readlane_b32 s21, v251, 11
	v_and_b32_e32 v34, 63, v2
	v_readlane_b32 s22, v251, 12
	v_readlane_b32 s23, v251, 13
	s_mov_b64 s[8:9], s[20:21]
	v_lshlrev_b32_e32 v202, 5, v34
	s_mov_b64 s[10:11], s[22:23]
	v_lshl_add_u64 v[26:27], s[10:11], 0, v[202:203]
	s_mov_b64 s[2:3], 0x1000
	v_lshl_add_u64 v[22:23], v[26:27], 0, s[2:3]
	s_mov_b64 s[2:3], 0x1800
	s_ashr_i32 s5, s4, 31
	v_lshl_add_u64 v[30:31], v[26:27], 0, s[2:3]
	s_lshl_b64 s[2:3], s[4:5], 12
	v_add_co_u32_e32 v28, vcc, 0x1000, v26
	s_add_u32 s2, s44, s2
	s_nop 0
	v_addc_co_u32_e32 v29, vcc, 0, v27, vcc
	s_addc_u32 s3, s45, s3
	v_lshlrev_b32_e32 v34, 4, v34
	global_load_dwordx4 v[2:5], v202, s[10:11] offset:16
	global_load_dwordx4 v[6:9], v202, s[10:11]
	global_load_dwordx4 v[10:13], v202, s[10:11] offset:2064
	global_load_dwordx4 v[14:17], v202, s[10:11] offset:2048
	global_load_dwordx4 v[18:21], v[28:29], off
	s_nop 0
	global_load_dwordx4 v[22:25], v[22:23], off offset:16
	s_nop 0
	global_load_dwordx4 v[26:29], v[28:29], off offset:2048
	s_nop 0
	global_load_dwordx4 v[30:33], v[30:31], off offset:16
	s_nop 0
	global_load_dwordx4 v[62:65], v34, s[2:3] nt
	global_load_dwordx4 v[58:61], v34, s[2:3] offset:1024 nt
	global_load_dwordx4 v[54:57], v34, s[2:3] offset:2048 nt
	global_load_dwordx4 v[50:53], v34, s[2:3] offset:3072 nt
	v_and_b32_e32 v36, 64, v237
	v_add_u32_e32 v36, 64, v36
	v_xor_b32_e32 v37, 1, v237
	v_cmp_lt_i32_e32 vcc, v37, v36
	s_ashr_i32 s1, s0, 31
	v_readlane_b32 s2, v254, 50
	v_cndmask_b32_e32 v37, v237, v37, vcc
	v_lshlrev_b32_e32 v70, 2, v37
	v_xor_b32_e32 v37, 2, v237
	v_cmp_lt_i32_e32 vcc, v37, v36
	s_add_u32 s2, s2, s0
	v_readlane_b32 s3, v254, 29
	v_cndmask_b32_e32 v37, v237, v37, vcc
	v_lshlrev_b32_e32 v71, 2, v37
	v_xor_b32_e32 v37, 4, v237
	v_cmp_lt_i32_e32 vcc, v37, v36
	s_addc_u32 s3, s3, s1
	s_lshl_b64 s[2:3], s[2:3], 13
	v_cndmask_b32_e32 v37, v237, v37, vcc
	v_lshlrev_b32_e32 v72, 2, v37
	v_xor_b32_e32 v37, 8, v237
	v_readlane_b32 s1, v254, 48
	v_cmp_lt_i32_e32 vcc, v37, v36
	s_add_u32 s2, s1, s2
	v_readlane_b32 s1, v254, 49
	v_cndmask_b32_e32 v37, v237, v37, vcc
	s_addc_u32 s3, s1, s3
	v_readlane_b32 s1, v254, 51
	v_lshlrev_b32_e32 v73, 2, v37
	v_xor_b32_e32 v37, 16, v237
	s_add_i32 s0, s1, s0
	v_cmp_lt_i32_e32 vcc, v37, v36
	s_ashr_i32 s1, s0, 31
	s_lshl_b64 s[0:1], s[0:1], 12
	v_cndmask_b32_e32 v37, v237, v37, vcc
	v_lshlrev_b32_e32 v74, 2, v37
	v_xor_b32_e32 v37, 32, v237
	s_add_u32 s0, s44, s0
	v_mov_b32_e32 v35, v203
	v_cmp_lt_i32_e32 vcc, v37, v36
	s_addc_u32 s1, s45, s1
	v_lshl_add_u64 v[68:69], s[0:1], 0, v[34:35]
	v_cndmask_b32_e32 v36, v237, v37, vcc
	v_mov_b32_e32 v34, 0
	v_lshlrev_b32_e32 v75, 2, v36
	v_lshl_add_u64 v[66:67], s[2:3], 0, v[202:203]
	v_mov_b32_e32 v35, v34
	v_mov_b32_e32 v36, v34
	v_mov_b32_e32 v37, v34
	v_mov_b32_e32 v38, v34
	v_mov_b32_e32 v39, v34
	v_mov_b32_e32 v40, v34
	v_mov_b32_e32 v41, v34
	v_mov_b32_e32 v42, v34
	v_mov_b32_e32 v43, v34
	v_mov_b32_e32 v44, v34
	v_mov_b32_e32 v45, v34
	v_mov_b32_e32 v46, v34
	v_mov_b32_e32 v47, v34
	v_mov_b32_e32 v48, v34
	v_mov_b32_e32 v49, v34
	v_readlane_b32 s17, v251, 7
	v_readlane_b32 s18, v251, 8
	v_readlane_b32 s19, v251, 9
	s_branch .LBB0_1795

.LBB0_1795:
	s_add_i32 s4, s4, s94
	s_cmpk_gt_i32 s4, 0x3fff
	s_cselect_b64 s[6:7], -1, 0
	s_and_b64 vcc, exec, s[6:7]
	s_cbranch_vccnz .LBB0_1794
	global_load_dwordx4 v[34:37], v[68:69], off nt
	global_load_dwordx4 v[38:41], v[68:69], off offset:1024 nt
	global_load_dwordx4 v[42:45], v[68:69], off offset:2048 nt
	global_load_dwordx4 v[46:49], v[68:69], off offset:3072 nt
	s_branch .LBB0_1794
